# adds a straight-line paired 16-byte-store path for the in-proj row-major (P) tile epilogue when the whole wave is below column 0x700; compiled code kept as fallback
# baseline (speedup 1.0000x reference)
;     __device__ __forceinline__ void fin(int m, int n, f32x4 v, f32x4, f32x4) const { horiz(m, n, v); }
;     __device__ __forceinline__ void fin(int m, int n, f32x4 v, f32x4, f32x4) const { horiz(m, n, v); }
; template <int MI, bool SWAP, class Epi> ...
;     ...
;     if (SWAP) {
; #pragma unroll
;         for (int i2 = 0; i2 < MI / 2; ++i2) {
;             f32x4 pa[2][4], pg[2][4];
; #pragma unroll
;             for (int ii = 0; ii < 2; ++ii)
; #pragma unroll
;                 for (int j = 0; j < 4; ++j) epi.pre(m0 + wr * (MI * 16) + (i2 * 2 + ii) * 16 + fr, n0 + wc * 64 + j * 16 + fq * 4, pa[ii][j], pg[ii][j]);
;             __builtin_amdgcn_sched_barrier(0);
; #pragma unroll
;             for (int ii = 0; ii < 2; ++ii)
; #pragma unroll
;                 for (int j = 0; j < 4; ++j) epi.fin(m0 + wr * (MI * 16) + (i2 * 2 + ii) * 16 + fr, n0 + wc * 64 + j * 16 + fq * 4, acc[i2 * 2 + ii][j], pa[ii][j], pg[ii][j]);
;         }
;     __device__ __forceinline__ void horiz(int m, int n, f32x4 v) const {
;         if (n < PW) {
;             u32x2 w; w.x = pack2(v[0], v[1]); w.y = pack2(v[2], v[3]);
;             *(u32x2*)(P + (size_t)m * PW + n) = w;
;         } else if (n >= 2816 && n < 2832) {
;             *(f32x4*)(G + (size_t)m * 16 + (n - 2816)) = v;
;         }
;     }
.LBB0_289:
	s_or_b32 s4, s24, s26
	s_cmp_le_u32 s4, 0x6c0
	s_cbranch_scc0 .Lslow_epi_inA
	v_or_b32_e32 v128, s18, v221
	v_add_u32_e32 v130, s23, v128
	v_lshl_or_b32 v128, v218, 2, s26
	v_or_b32_e32 v128, s24, v128
	v_mad_i64_i32 v[132:133], vcc, v130, s71, 0
	v_lshl_add_u64 v[132:133], s[68:69], 0, v[132:133]
	v_ashrrev_i32_e32 v129, 31, v128
	v_lshl_add_u64 v[130:131], v[128:129], 1, v[132:133]
	v_and_b32_e32 v128, 1, v218
	v_mul_u32_u24_e32 v128, 24, v128
	v_mov_b32_e32 v129, 0
	v_lshl_add_u64 v[130:131], v[130:131], 0, v[128:129]
	s_mov_b64 vcc, 0xe000
	v_cvt_pk_bf16_f32 v124, v124, v125
	v_cvt_pk_bf16_f32 v125, v126, v127
	v_cvt_pk_bf16_f32 v126, v120, v121
	v_cvt_pk_bf16_f32 v127, v122, v123
	v_cvt_pk_bf16_f32 v116, v116, v117
	v_cvt_pk_bf16_f32 v117, v118, v119
	v_cvt_pk_bf16_f32 v118, v112, v113
	v_cvt_pk_bf16_f32 v119, v114, v115
	s_nop 1
	v_permlane16_swap_b32_e32 v124, v126
	v_permlane16_swap_b32_e32 v125, v127
	v_permlane16_swap_b32_e32 v116, v118
	v_permlane16_swap_b32_e32 v117, v119
	v_lshl_add_u64 v[132:133], v[130:131], 0, vcc
	s_nop 0
	global_store_dwordx4 v[130:131], v[124:127], off
	global_store_dwordx4 v[130:131], v[116:119], off offset:64
	v_cvt_pk_bf16_f32 v108, v108, v109
	v_cvt_pk_bf16_f32 v109, v110, v111
	v_cvt_pk_bf16_f32 v110, v104, v105
	v_cvt_pk_bf16_f32 v111, v106, v107
	v_cvt_pk_bf16_f32 v100, v100, v101
	v_cvt_pk_bf16_f32 v101, v102, v103
	v_cvt_pk_bf16_f32 v102, v96, v97
	v_cvt_pk_bf16_f32 v103, v98, v99
	s_nop 1
	v_permlane16_swap_b32_e32 v108, v110
	v_permlane16_swap_b32_e32 v109, v111
	v_permlane16_swap_b32_e32 v100, v102
	v_permlane16_swap_b32_e32 v101, v103
	v_lshl_add_u64 v[130:131], v[132:133], 0, vcc
	s_nop 0
	global_store_dwordx4 v[132:133], v[108:111], off
	global_store_dwordx4 v[132:133], v[100:103], off offset:64
	v_cvt_pk_bf16_f32 v92, v92, v93
	v_cvt_pk_bf16_f32 v93, v94, v95
	v_cvt_pk_bf16_f32 v94, v88, v89
	v_cvt_pk_bf16_f32 v95, v90, v91
	v_cvt_pk_bf16_f32 v84, v84, v85
	v_cvt_pk_bf16_f32 v85, v86, v87
	v_cvt_pk_bf16_f32 v86, v80, v81
	v_cvt_pk_bf16_f32 v87, v82, v83
	s_nop 1
	v_permlane16_swap_b32_e32 v92, v94
	v_permlane16_swap_b32_e32 v93, v95
	v_permlane16_swap_b32_e32 v84, v86
	v_permlane16_swap_b32_e32 v85, v87
	v_lshl_add_u64 v[132:133], v[130:131], 0, vcc
	s_nop 0
	global_store_dwordx4 v[130:131], v[92:95], off
	global_store_dwordx4 v[130:131], v[84:87], off offset:64
	v_cvt_pk_bf16_f32 v76, v76, v77
	v_cvt_pk_bf16_f32 v77, v78, v79
	v_cvt_pk_bf16_f32 v78, v72, v73
	v_cvt_pk_bf16_f32 v79, v74, v75
	v_cvt_pk_bf16_f32 v68, v68, v69
	v_cvt_pk_bf16_f32 v69, v70, v71
	v_cvt_pk_bf16_f32 v70, v64, v65
	v_cvt_pk_bf16_f32 v71, v66, v67
	s_nop 1
	v_permlane16_swap_b32_e32 v76, v78
	v_permlane16_swap_b32_e32 v77, v79
	v_permlane16_swap_b32_e32 v68, v70
	v_permlane16_swap_b32_e32 v69, v71
	v_lshl_add_u64 v[130:131], v[132:133], 0, vcc
	s_nop 0
	global_store_dwordx4 v[132:133], v[76:79], off
	global_store_dwordx4 v[132:133], v[68:71], off offset:64
	v_cvt_pk_bf16_f32 v60, v60, v61
	v_cvt_pk_bf16_f32 v61, v62, v63
	v_cvt_pk_bf16_f32 v62, v56, v57
	v_cvt_pk_bf16_f32 v63, v58, v59
	v_cvt_pk_bf16_f32 v52, v52, v53
	v_cvt_pk_bf16_f32 v53, v54, v55
	v_cvt_pk_bf16_f32 v54, v48, v49
	v_cvt_pk_bf16_f32 v55, v50, v51
	s_nop 1
	v_permlane16_swap_b32_e32 v60, v62
	v_permlane16_swap_b32_e32 v61, v63
	v_permlane16_swap_b32_e32 v52, v54
	v_permlane16_swap_b32_e32 v53, v55
	v_lshl_add_u64 v[132:133], v[130:131], 0, vcc
	s_nop 0
	global_store_dwordx4 v[130:131], v[60:63], off
	global_store_dwordx4 v[130:131], v[52:55], off offset:64
	v_cvt_pk_bf16_f32 v44, v44, v45
	v_cvt_pk_bf16_f32 v45, v46, v47
	v_cvt_pk_bf16_f32 v46, v40, v41
	v_cvt_pk_bf16_f32 v47, v42, v43
	v_cvt_pk_bf16_f32 v36, v36, v37
	v_cvt_pk_bf16_f32 v37, v38, v39
	v_cvt_pk_bf16_f32 v38, v32, v33
	v_cvt_pk_bf16_f32 v39, v34, v35
	s_nop 1
	v_permlane16_swap_b32_e32 v44, v46
	v_permlane16_swap_b32_e32 v45, v47
	v_permlane16_swap_b32_e32 v36, v38
	v_permlane16_swap_b32_e32 v37, v39
	v_lshl_add_u64 v[130:131], v[132:133], 0, vcc
	s_nop 0
	global_store_dwordx4 v[132:133], v[44:47], off
	global_store_dwordx4 v[132:133], v[36:39], off offset:64
	v_cvt_pk_bf16_f32 v28, v28, v29
	v_cvt_pk_bf16_f32 v29, v30, v31
	v_cvt_pk_bf16_f32 v30, v24, v25
	v_cvt_pk_bf16_f32 v31, v26, v27
	v_cvt_pk_bf16_f32 v20, v20, v21
	v_cvt_pk_bf16_f32 v21, v22, v23
	v_cvt_pk_bf16_f32 v22, v16, v17
	v_cvt_pk_bf16_f32 v23, v18, v19
	s_nop 1
	v_permlane16_swap_b32_e32 v28, v30
	v_permlane16_swap_b32_e32 v29, v31
	v_permlane16_swap_b32_e32 v20, v22
	v_permlane16_swap_b32_e32 v21, v23
	v_lshl_add_u64 v[132:133], v[130:131], 0, vcc
	s_nop 0
	global_store_dwordx4 v[130:131], v[28:31], off
	global_store_dwordx4 v[130:131], v[20:23], off offset:64
	v_cvt_pk_bf16_f32 v12, v12, v13
	v_cvt_pk_bf16_f32 v13, v14, v15
	v_cvt_pk_bf16_f32 v14, v8, v9
	v_cvt_pk_bf16_f32 v15, v10, v11
	v_cvt_pk_bf16_f32 v4, v4, v5
	v_cvt_pk_bf16_f32 v5, v6, v7
	v_cvt_pk_bf16_f32 v6, v0, v1
	v_cvt_pk_bf16_f32 v7, v2, v3
	s_nop 1
	v_permlane16_swap_b32_e32 v12, v14
	v_permlane16_swap_b32_e32 v13, v15
	v_permlane16_swap_b32_e32 v4, v6
	v_permlane16_swap_b32_e32 v5, v7
	s_nop 0
	global_store_dwordx4 v[132:133], v[12:15], off
	global_store_dwordx4 v[132:133], v[4:7], off offset:64
	s_branch .LBB0_253

;     __device__ __forceinline__ void fin(int m, int n, f32x4 v, f32x4, f32x4) const { horiz(m, n, v); }
;     __device__ __forceinline__ void fin(int m, int n, f32x4 v, f32x4, f32x4) const { horiz(m, n, v); }
; template <int MI, bool SWAP, class Epi> ...
;     ...
;     if (SWAP) {
; #pragma unroll
;         for (int i2 = 0; i2 < MI / 2; ++i2) {
;             f32x4 pa[2][4], pg[2][4];
; #pragma unroll
;             for (int ii = 0; ii < 2; ++ii)
; #pragma unroll
;                 for (int j = 0; j < 4; ++j) epi.pre(m0 + wr * (MI * 16) + (i2 * 2 + ii) * 16 + fr, n0 + wc * 64 + j * 16 + fq * 4, pa[ii][j], pg[ii][j]);
;             __builtin_amdgcn_sched_barrier(0);
; #pragma unroll
;             for (int ii = 0; ii < 2; ++ii)
; #pragma unroll
;                 for (int j = 0; j < 4; ++j) epi.fin(m0 + wr * (MI * 16) + (i2 * 2 + ii) * 16 + fr, n0 + wc * 64 + j * 16 + fq * 4, acc[i2 * 2 + ii][j], pa[ii][j], pg[ii][j]);
;         }
.LBB0_1990:
	v_or_b32_e32 v128, s22, v221
	v_add_u32_e32 v130, s26, v128
	v_lshl_or_b32 v128, v218, 2, s11
	v_or_b32_e32 v128, s27, v128
	s_mov_b32 s4, 0x8000
	v_readlane_b32 s6, v252, 20
	v_readlane_b32 s0, v252, 18
	v_readlane_b32 s7, v252, 21
	v_readlane_b32 s1, v252, 19
	v_readlane_b32 s24, v248, 47
	v_readlane_b32 s26, v248, 49
	v_readlane_b32 s27, v248, 50
	v_readlane_b32 s5, v250, 4
	v_readlane_b32 s25, v248, 48
	v_readlane_b32 s28, v248, 51
	v_readlane_b32 s29, v248, 52
	v_readlane_b32 s30, v248, 53
	v_readlane_b32 s31, v248, 54
	v_ashrrev_i32_e32 v129, 31, v128
	v_lshlrev_b64 v[128:129], 2, v[128:129]
	v_min_i32_e32 v131, 0x8000, v130
	v_ashrrev_i32_e32 v131, 11, v131
	v_mul_hi_i32_i24_e32 v133, 0x6000, v131
	v_mul_i32_i24_e32 v132, 0x6000, v131
	v_lshl_add_u64 v[132:133], s[14:15], 0, v[132:133]
	v_lshl_add_u64 v[132:133], v[132:133], 0, v[128:129]
	v_mov_b32_e32 v131, 0
	v_lshlrev_b64 v[130:131], 12, v[130:131]
	v_lshl_add_u64 v[134:135], s[0:1], 0, v[130:131]
	v_lshl_add_u64 v[134:135], v[134:135], 0, v[128:129]
	v_lshl_add_u64 v[136:137], s[26:27], 0, v[130:131]
	v_lshl_add_u64 v[136:137], v[136:137], 0, v[128:129]
	s_mov_b64 vcc, 0x10000
	global_load_dwordx4 v[140:143], v[132:133], off
	global_load_dwordx4 v[144:147], v[132:133], off offset:64
	global_load_dwordx4 v[148:151], v[132:133], off offset:128
	global_load_dwordx4 v[152:155], v[132:133], off offset:192
	global_load_dwordx4 v[156:159], v[134:135], off
	global_load_dwordx4 v[160:163], v[134:135], off offset:64
	global_load_dwordx4 v[164:167], v[134:135], off offset:128
	global_load_dwordx4 v[168:171], v[134:135], off offset:192
	s_nop 0
	v_lshl_add_u64 v[134:135], v[134:135], 0, vcc
	global_load_dwordx4 v[172:175], v[134:135], off
	global_load_dwordx4 v[176:179], v[134:135], off offset:64
	global_load_dwordx4 v[220:223], v[134:135], off offset:128
	global_load_dwordx4 v[224:227], v[134:135], off offset:192
	s_nop 0
	v_lshl_add_u64 v[134:135], v[134:135], 0, vcc
	global_load_dwordx4 v[228:231], v[134:135], off
	global_load_dwordx4 v[232:235], v[134:135], off offset:64
	global_load_dwordx4 v[236:239], v[134:135], off offset:128
	global_load_dwordx4 v[240:243], v[134:135], off offset:192
	s_nop 0
	v_lshl_add_u64 v[134:135], v[134:135], 0, vcc
	s_waitcnt vmcnt(8)
	v_pk_fma_f32 v[124:125], v[124:125], v[140:141], v[156:157]
	v_pk_fma_f32 v[126:127], v[126:127], v[142:143], v[158:159]
	v_pk_fma_f32 v[120:121], v[120:121], v[144:145], v[160:161]
	v_pk_fma_f32 v[122:123], v[122:123], v[146:147], v[162:163]
	v_pk_fma_f32 v[116:117], v[116:117], v[148:149], v[164:165]
	v_pk_fma_f32 v[118:119], v[118:119], v[150:151], v[166:167]
	v_pk_fma_f32 v[112:113], v[112:113], v[152:153], v[168:169]
	v_pk_fma_f32 v[114:115], v[114:115], v[154:155], v[170:171]
	global_store_dwordx4 v[136:137], v[124:127], off
	global_store_dwordx4 v[136:137], v[120:123], off offset:64
	global_store_dwordx4 v[136:137], v[116:119], off offset:128
	global_store_dwordx4 v[136:137], v[112:115], off offset:192
	s_nop 1
	v_lshl_add_u64 v[136:137], v[136:137], 0, vcc
	global_load_dwordx4 v[156:159], v[134:135], off
	global_load_dwordx4 v[160:163], v[134:135], off offset:64
	global_load_dwordx4 v[164:167], v[134:135], off offset:128
	global_load_dwordx4 v[168:171], v[134:135], off offset:192
	s_nop 0
	v_lshl_add_u64 v[134:135], v[134:135], 0, vcc
	s_waitcnt vmcnt(12)
	v_pk_fma_f32 v[108:109], v[108:109], v[140:141], v[172:173]
	v_pk_fma_f32 v[110:111], v[110:111], v[142:143], v[174:175]
	v_pk_fma_f32 v[104:105], v[104:105], v[144:145], v[176:177]
	v_pk_fma_f32 v[106:107], v[106:107], v[146:147], v[178:179]
	v_pk_fma_f32 v[100:101], v[100:101], v[148:149], v[220:221]
	v_pk_fma_f32 v[102:103], v[102:103], v[150:151], v[222:223]
	v_pk_fma_f32 v[96:97], v[96:97], v[152:153], v[224:225]
	v_pk_fma_f32 v[98:99], v[98:99], v[154:155], v[226:227]
	global_store_dwordx4 v[136:137], v[108:111], off
	global_store_dwordx4 v[136:137], v[104:107], off offset:64
	global_store_dwordx4 v[136:137], v[100:103], off offset:128
	global_store_dwordx4 v[136:137], v[96:99], off offset:192
	s_nop 1
	v_lshl_add_u64 v[136:137], v[136:137], 0, vcc
	global_load_dwordx4 v[172:175], v[134:135], off
	global_load_dwordx4 v[176:179], v[134:135], off offset:64
	global_load_dwordx4 v[220:223], v[134:135], off offset:128
	global_load_dwordx4 v[224:227], v[134:135], off offset:192
	s_nop 0
	v_lshl_add_u64 v[134:135], v[134:135], 0, vcc
	s_waitcnt vmcnt(16)
;     __device__ __forceinline__ void fin(int m, int n, f32x4 v, f32x4, f32x4) const { horiz(m, n, v); }
;     __device__ __forceinline__ void fin(int m, int n, f32x4 v, f32x4, f32x4) const { horiz(m, n, v); }
; template <int MI, bool SWAP, class Epi> ...
;     ...
;     if (SWAP) {
; #pragma unroll
;         for (int i2 = 0; i2 < MI / 2; ++i2) {
;             f32x4 pa[2][4], pg[2][4];
; #pragma unroll
;             for (int ii = 0; ii < 2; ++ii)
; #pragma unroll
;                 for (int j = 0; j < 4; ++j) epi.pre(m0 + wr * (MI * 16) + (i2 * 2 + ii) * 16 + fr, n0 + wc * 64 + j * 16 + fq * 4, pa[ii][j], pg[ii][j]);
;             __builtin_amdgcn_sched_barrier(0);
; #pragma unroll
;             for (int ii = 0; ii < 2; ++ii)
; #pragma unroll
;                 for (int j = 0; j < 4; ++j) epi.fin(m0 + wr * (MI * 16) + (i2 * 2 + ii) * 16 + fr, n0 + wc * 64 + j * 16 + fq * 4, acc[i2 * 2 + ii][j], pa[ii][j], pg[ii][j]);
;         }
	v_pk_fma_f32 v[92:93], v[92:93], v[140:141], v[228:229]
	v_pk_fma_f32 v[94:95], v[94:95], v[142:143], v[230:231]
	v_pk_fma_f32 v[88:89], v[88:89], v[144:145], v[232:233]
	v_pk_fma_f32 v[90:91], v[90:91], v[146:147], v[234:235]
	v_pk_fma_f32 v[84:85], v[84:85], v[148:149], v[236:237]
	v_pk_fma_f32 v[86:87], v[86:87], v[150:151], v[238:239]
	v_pk_fma_f32 v[80:81], v[80:81], v[152:153], v[240:241]
	v_pk_fma_f32 v[82:83], v[82:83], v[154:155], v[242:243]
	global_store_dwordx4 v[136:137], v[92:95], off
	global_store_dwordx4 v[136:137], v[88:91], off offset:64
	global_store_dwordx4 v[136:137], v[84:87], off offset:128
	global_store_dwordx4 v[136:137], v[80:83], off offset:192
	s_nop 1
	v_lshl_add_u64 v[136:137], v[136:137], 0, vcc
	global_load_dwordx4 v[228:231], v[134:135], off
	global_load_dwordx4 v[232:235], v[134:135], off offset:64
	global_load_dwordx4 v[236:239], v[134:135], off offset:128
	global_load_dwordx4 v[240:243], v[134:135], off offset:192
	s_nop 0
	v_lshl_add_u64 v[134:135], v[134:135], 0, vcc
	s_waitcnt vmcnt(16)
	v_pk_fma_f32 v[76:77], v[76:77], v[140:141], v[156:157]
	v_pk_fma_f32 v[78:79], v[78:79], v[142:143], v[158:159]
	v_pk_fma_f32 v[72:73], v[72:73], v[144:145], v[160:161]
	v_pk_fma_f32 v[74:75], v[74:75], v[146:147], v[162:163]
	v_pk_fma_f32 v[68:69], v[68:69], v[148:149], v[164:165]
	v_pk_fma_f32 v[70:71], v[70:71], v[150:151], v[166:167]
	v_pk_fma_f32 v[64:65], v[64:65], v[152:153], v[168:169]
	v_pk_fma_f32 v[66:67], v[66:67], v[154:155], v[170:171]
	global_store_dwordx4 v[136:137], v[76:79], off
	global_store_dwordx4 v[136:137], v[72:75], off offset:64
	global_store_dwordx4 v[136:137], v[68:71], off offset:128
	global_store_dwordx4 v[136:137], v[64:67], off offset:192
	s_nop 1
	v_lshl_add_u64 v[136:137], v[136:137], 0, vcc
	global_load_dwordx4 v[156:159], v[134:135], off
	global_load_dwordx4 v[160:163], v[134:135], off offset:64
	global_load_dwordx4 v[164:167], v[134:135], off offset:128
	global_load_dwordx4 v[168:171], v[134:135], off offset:192
	s_nop 0
	v_lshl_add_u64 v[134:135], v[134:135], 0, vcc
	s_waitcnt vmcnt(16)
	v_pk_fma_f32 v[60:61], v[60:61], v[140:141], v[172:173]
	v_pk_fma_f32 v[62:63], v[62:63], v[142:143], v[174:175]
	v_pk_fma_f32 v[56:57], v[56:57], v[144:145], v[176:177]
	v_pk_fma_f32 v[58:59], v[58:59], v[146:147], v[178:179]
	v_pk_fma_f32 v[52:53], v[52:53], v[148:149], v[220:221]
	v_pk_fma_f32 v[54:55], v[54:55], v[150:151], v[222:223]
	v_pk_fma_f32 v[48:49], v[48:49], v[152:153], v[224:225]
	v_pk_fma_f32 v[50:51], v[50:51], v[154:155], v[226:227]
	global_store_dwordx4 v[136:137], v[60:63], off
	global_store_dwordx4 v[136:137], v[56:59], off offset:64
	global_store_dwordx4 v[136:137], v[52:55], off offset:128
	global_store_dwordx4 v[136:137], v[48:51], off offset:192
	s_nop 1
	v_lshl_add_u64 v[136:137], v[136:137], 0, vcc
	global_load_dwordx4 v[172:175], v[134:135], off
	global_load_dwordx4 v[176:179], v[134:135], off offset:64
	global_load_dwordx4 v[220:223], v[134:135], off offset:128
	global_load_dwordx4 v[224:227], v[134:135], off offset:192
	s_waitcnt vmcnt(16)
	v_pk_fma_f32 v[44:45], v[44:45], v[140:141], v[228:229]
	v_pk_fma_f32 v[46:47], v[46:47], v[142:143], v[230:231]
	v_pk_fma_f32 v[40:41], v[40:41], v[144:145], v[232:233]
	v_pk_fma_f32 v[42:43], v[42:43], v[146:147], v[234:235]
	v_pk_fma_f32 v[36:37], v[36:37], v[148:149], v[236:237]
	v_pk_fma_f32 v[38:39], v[38:39], v[150:151], v[238:239]
	v_pk_fma_f32 v[32:33], v[32:33], v[152:153], v[240:241]
	v_pk_fma_f32 v[34:35], v[34:35], v[154:155], v[242:243]
	global_store_dwordx4 v[136:137], v[44:47], off
	global_store_dwordx4 v[136:137], v[40:43], off offset:64
	global_store_dwordx4 v[136:137], v[36:39], off offset:128
	global_store_dwordx4 v[136:137], v[32:35], off offset:192
	s_nop 1
	v_lshl_add_u64 v[136:137], v[136:137], 0, vcc
	s_waitcnt vmcnt(12)
	v_pk_fma_f32 v[28:29], v[28:29], v[140:141], v[156:157]
	v_pk_fma_f32 v[30:31], v[30:31], v[142:143], v[158:159]
	v_pk_fma_f32 v[24:25], v[24:25], v[144:145], v[160:161]
	v_pk_fma_f32 v[26:27], v[26:27], v[146:147], v[162:163]
	v_pk_fma_f32 v[20:21], v[20:21], v[148:149], v[164:165]
	v_pk_fma_f32 v[22:23], v[22:23], v[150:151], v[166:167]
	v_pk_fma_f32 v[16:17], v[16:17], v[152:153], v[168:169]
	v_pk_fma_f32 v[18:19], v[18:19], v[154:155], v[170:171]
	global_store_dwordx4 v[136:137], v[28:31], off
	global_store_dwordx4 v[136:137], v[24:27], off offset:64
	global_store_dwordx4 v[136:137], v[20:23], off offset:128
	global_store_dwordx4 v[136:137], v[16:19], off offset:192
	s_nop 1
	v_lshl_add_u64 v[136:137], v[136:137], 0, vcc
	s_waitcnt vmcnt(8)
	v_pk_fma_f32 v[12:13], v[12:13], v[140:141], v[172:173]
	v_pk_fma_f32 v[14:15], v[14:15], v[142:143], v[174:175]
	v_pk_fma_f32 v[8:9], v[8:9], v[144:145], v[176:177]
	v_pk_fma_f32 v[10:11], v[10:11], v[146:147], v[178:179]
	v_pk_fma_f32 v[4:5], v[4:5], v[148:149], v[220:221]
	v_pk_fma_f32 v[6:7], v[6:7], v[150:151], v[222:223]
	v_pk_fma_f32 v[0:1], v[0:1], v[152:153], v[224:225]
	v_pk_fma_f32 v[2:3], v[2:3], v[154:155], v[226:227]
	global_store_dwordx4 v[136:137], v[12:15], off
	global_store_dwordx4 v[136:137], v[8:11], off offset:64
	global_store_dwordx4 v[136:137], v[4:7], off offset:128
	global_store_dwordx4 v[136:137], v[0:3], off offset:192
	s_andn2_b64 vcc, exec, s[2:3]
	s_mov_b64 s[22:23], -1
	s_cbranch_vccz .LBB0_1992
	s_mov_b32 s72, s10
	s_mov_b32 s70, s18
	s_branch .LBB0_1947

;     __device__ __forceinline__ void fin(int m, int n, f32x4 v, f32x4, f32x4) const { horiz(m, n, v); }
;     __device__ __forceinline__ void fin(int m, int n, f32x4 v, f32x4, f32x4) const { horiz(m, n, v); }
; template <int MI, bool SWAP, class Epi> ...
;     ...
;     if (SWAP) {
; #pragma unroll
;         for (int i2 = 0; i2 < MI / 2; ++i2) {
;             f32x4 pa[2][4], pg[2][4];
; #pragma unroll
;             for (int ii = 0; ii < 2; ++ii)
; #pragma unroll
;                 for (int j = 0; j < 4; ++j) epi.pre(m0 + wr * (MI * 16) + (i2 * 2 + ii) * 16 + fr, n0 + wc * 64 + j * 16 + fq * 4, pa[ii][j], pg[ii][j]);
;             __builtin_amdgcn_sched_barrier(0);
; #pragma unroll
;             for (int ii = 0; ii < 2; ++ii)
; #pragma unroll
;                 for (int j = 0; j < 4; ++j) epi.fin(m0 + wr * (MI * 16) + (i2 * 2 + ii) * 16 + fr, n0 + wc * 64 + j * 16 + fq * 4, acc[i2 * 2 + ii][j], pa[ii][j], pg[ii][j]);
;         }
.LBB0_2322:
	v_or_b32_e32 v128, s24, v221
	v_add_u32_e32 v130, s28, v128
	v_lshl_or_b32 v128, v218, 2, s11
	v_or_b32_e32 v128, s29, v128
	s_mov_b32 s0, 0x8000
	v_readlane_b32 s24, v248, 47
	v_readlane_b32 s26, v248, 49
	v_readlane_b32 s27, v248, 50
	v_readlane_b32 s1, v250, 4
	v_readlane_b32 s25, v248, 48
	v_readlane_b32 s28, v248, 51
	v_readlane_b32 s29, v248, 52
	v_readlane_b32 s30, v248, 53
	v_readlane_b32 s31, v248, 54
	v_ashrrev_i32_e32 v129, 31, v128
	v_lshlrev_b64 v[128:129], 2, v[128:129]
	v_min_i32_e32 v131, 0x8000, v130
	v_ashrrev_i32_e32 v131, 11, v131
	v_mul_hi_i32_i24_e32 v133, 0x6000, v131
	v_mul_i32_i24_e32 v132, 0x6000, v131
	v_lshl_add_u64 v[132:133], s[16:17], 0, v[132:133]
	v_lshl_add_u64 v[132:133], v[132:133], 0, v[128:129]
	v_mov_b32_e32 v131, 0
	v_lshlrev_b64 v[130:131], 12, v[130:131]
	v_lshl_add_u64 v[134:135], s[26:27], 0, v[130:131]
	v_lshl_add_u64 v[134:135], v[134:135], 0, v[128:129]
	v_lshl_add_u64 v[136:137], s[26:27], 0, v[130:131]
	v_lshl_add_u64 v[136:137], v[136:137], 0, v[128:129]
	s_mov_b64 vcc, 0x10000
	global_load_dwordx4 v[140:143], v[132:133], off
	global_load_dwordx4 v[144:147], v[132:133], off offset:64
	global_load_dwordx4 v[148:151], v[132:133], off offset:128
	global_load_dwordx4 v[152:155], v[132:133], off offset:192
	global_load_dwordx4 v[156:159], v[134:135], off
	global_load_dwordx4 v[160:163], v[134:135], off offset:64
	global_load_dwordx4 v[164:167], v[134:135], off offset:128
	global_load_dwordx4 v[168:171], v[134:135], off offset:192
	s_nop 0
	v_lshl_add_u64 v[134:135], v[134:135], 0, vcc
	global_load_dwordx4 v[172:175], v[134:135], off
	global_load_dwordx4 v[176:179], v[134:135], off offset:64
	global_load_dwordx4 v[220:223], v[134:135], off offset:128
	global_load_dwordx4 v[224:227], v[134:135], off offset:192
	s_nop 0
	v_lshl_add_u64 v[134:135], v[134:135], 0, vcc
	global_load_dwordx4 v[228:231], v[134:135], off
	global_load_dwordx4 v[232:235], v[134:135], off offset:64
	global_load_dwordx4 v[236:239], v[134:135], off offset:128
	global_load_dwordx4 v[240:243], v[134:135], off offset:192
	s_nop 0
	v_lshl_add_u64 v[134:135], v[134:135], 0, vcc
	s_waitcnt vmcnt(8)
	v_pk_fma_f32 v[124:125], v[124:125], v[140:141], v[156:157]
	v_pk_fma_f32 v[126:127], v[126:127], v[142:143], v[158:159]
	v_pk_fma_f32 v[120:121], v[120:121], v[144:145], v[160:161]
	v_pk_fma_f32 v[122:123], v[122:123], v[146:147], v[162:163]
	v_pk_fma_f32 v[116:117], v[116:117], v[148:149], v[164:165]
	v_pk_fma_f32 v[118:119], v[118:119], v[150:151], v[166:167]
	v_pk_fma_f32 v[112:113], v[112:113], v[152:153], v[168:169]
	v_pk_fma_f32 v[114:115], v[114:115], v[154:155], v[170:171]
	global_store_dwordx4 v[136:137], v[124:127], off
	global_store_dwordx4 v[136:137], v[120:123], off offset:64
	global_store_dwordx4 v[136:137], v[116:119], off offset:128
	global_store_dwordx4 v[136:137], v[112:115], off offset:192
	s_nop 1
	v_lshl_add_u64 v[136:137], v[136:137], 0, vcc
	global_load_dwordx4 v[156:159], v[134:135], off
	global_load_dwordx4 v[160:163], v[134:135], off offset:64
	global_load_dwordx4 v[164:167], v[134:135], off offset:128
	global_load_dwordx4 v[168:171], v[134:135], off offset:192
	s_nop 0
	v_lshl_add_u64 v[134:135], v[134:135], 0, vcc
	s_waitcnt vmcnt(12)
	v_pk_fma_f32 v[108:109], v[108:109], v[140:141], v[172:173]
	v_pk_fma_f32 v[110:111], v[110:111], v[142:143], v[174:175]
	v_pk_fma_f32 v[104:105], v[104:105], v[144:145], v[176:177]
	v_pk_fma_f32 v[106:107], v[106:107], v[146:147], v[178:179]
	v_pk_fma_f32 v[100:101], v[100:101], v[148:149], v[220:221]
	v_pk_fma_f32 v[102:103], v[102:103], v[150:151], v[222:223]
	v_pk_fma_f32 v[96:97], v[96:97], v[152:153], v[224:225]
	v_pk_fma_f32 v[98:99], v[98:99], v[154:155], v[226:227]
	global_store_dwordx4 v[136:137], v[108:111], off
	global_store_dwordx4 v[136:137], v[104:107], off offset:64
	global_store_dwordx4 v[136:137], v[100:103], off offset:128
	global_store_dwordx4 v[136:137], v[96:99], off offset:192
	s_nop 1
	v_lshl_add_u64 v[136:137], v[136:137], 0, vcc
	global_load_dwordx4 v[172:175], v[134:135], off
	global_load_dwordx4 v[176:179], v[134:135], off offset:64
	global_load_dwordx4 v[220:223], v[134:135], off offset:128
	global_load_dwordx4 v[224:227], v[134:135], off offset:192
	s_nop 0
	v_lshl_add_u64 v[134:135], v[134:135], 0, vcc
	s_waitcnt vmcnt(16)
	v_pk_fma_f32 v[92:93], v[92:93], v[140:141], v[228:229]
	v_pk_fma_f32 v[94:95], v[94:95], v[142:143], v[230:231]
	v_pk_fma_f32 v[88:89], v[88:89], v[144:145], v[232:233]
	v_pk_fma_f32 v[90:91], v[90:91], v[146:147], v[234:235]
	v_pk_fma_f32 v[84:85], v[84:85], v[148:149], v[236:237]
	v_pk_fma_f32 v[86:87], v[86:87], v[150:151], v[238:239]
	v_pk_fma_f32 v[80:81], v[80:81], v[152:153], v[240:241]
	v_pk_fma_f32 v[82:83], v[82:83], v[154:155], v[242:243]
	global_store_dwordx4 v[136:137], v[92:95], off
	global_store_dwordx4 v[136:137], v[88:91], off offset:64
	global_store_dwordx4 v[136:137], v[84:87], off offset:128
	global_store_dwordx4 v[136:137], v[80:83], off offset:192
	s_nop 1
	v_lshl_add_u64 v[136:137], v[136:137], 0, vcc
	global_load_dwordx4 v[228:231], v[134:135], off
	global_load_dwordx4 v[232:235], v[134:135], off offset:64
	global_load_dwordx4 v[236:239], v[134:135], off offset:128
	global_load_dwordx4 v[240:243], v[134:135], off offset:192
	s_nop 0
	v_lshl_add_u64 v[134:135], v[134:135], 0, vcc
	s_waitcnt vmcnt(16)
;     __device__ __forceinline__ void fin(int m, int n, f32x4 v, f32x4, f32x4) const { horiz(m, n, v); }
;     __device__ __forceinline__ void fin(int m, int n, f32x4 v, f32x4, f32x4) const { horiz(m, n, v); }
; template <int MI, bool SWAP, class Epi> ...
;     ...
;     if (SWAP) {
; #pragma unroll
;         for (int i2 = 0; i2 < MI / 2; ++i2) {
;             f32x4 pa[2][4], pg[2][4];
; #pragma unroll
;             for (int ii = 0; ii < 2; ++ii)
; #pragma unroll
;                 for (int j = 0; j < 4; ++j) epi.pre(m0 + wr * (MI * 16) + (i2 * 2 + ii) * 16 + fr, n0 + wc * 64 + j * 16 + fq * 4, pa[ii][j], pg[ii][j]);
;             __builtin_amdgcn_sched_barrier(0);
; #pragma unroll
;             for (int ii = 0; ii < 2; ++ii)
; #pragma unroll
;                 for (int j = 0; j < 4; ++j) epi.fin(m0 + wr * (MI * 16) + (i2 * 2 + ii) * 16 + fr, n0 + wc * 64 + j * 16 + fq * 4, acc[i2 * 2 + ii][j], pa[ii][j], pg[ii][j]);
;         }
	v_pk_fma_f32 v[76:77], v[76:77], v[140:141], v[156:157]
	v_pk_fma_f32 v[78:79], v[78:79], v[142:143], v[158:159]
	v_pk_fma_f32 v[72:73], v[72:73], v[144:145], v[160:161]
	v_pk_fma_f32 v[74:75], v[74:75], v[146:147], v[162:163]
	v_pk_fma_f32 v[68:69], v[68:69], v[148:149], v[164:165]
	v_pk_fma_f32 v[70:71], v[70:71], v[150:151], v[166:167]
	v_pk_fma_f32 v[64:65], v[64:65], v[152:153], v[168:169]
	v_pk_fma_f32 v[66:67], v[66:67], v[154:155], v[170:171]
	global_store_dwordx4 v[136:137], v[76:79], off
	global_store_dwordx4 v[136:137], v[72:75], off offset:64
	global_store_dwordx4 v[136:137], v[68:71], off offset:128
	global_store_dwordx4 v[136:137], v[64:67], off offset:192
	s_nop 1
	v_lshl_add_u64 v[136:137], v[136:137], 0, vcc
	global_load_dwordx4 v[156:159], v[134:135], off
	global_load_dwordx4 v[160:163], v[134:135], off offset:64
	global_load_dwordx4 v[164:167], v[134:135], off offset:128
	global_load_dwordx4 v[168:171], v[134:135], off offset:192
	s_nop 0
	v_lshl_add_u64 v[134:135], v[134:135], 0, vcc
	s_waitcnt vmcnt(16)
	v_pk_fma_f32 v[60:61], v[60:61], v[140:141], v[172:173]
	v_pk_fma_f32 v[62:63], v[62:63], v[142:143], v[174:175]
	v_pk_fma_f32 v[56:57], v[56:57], v[144:145], v[176:177]
	v_pk_fma_f32 v[58:59], v[58:59], v[146:147], v[178:179]
	v_pk_fma_f32 v[52:53], v[52:53], v[148:149], v[220:221]
	v_pk_fma_f32 v[54:55], v[54:55], v[150:151], v[222:223]
	v_pk_fma_f32 v[48:49], v[48:49], v[152:153], v[224:225]
	v_pk_fma_f32 v[50:51], v[50:51], v[154:155], v[226:227]
	global_store_dwordx4 v[136:137], v[60:63], off
	global_store_dwordx4 v[136:137], v[56:59], off offset:64
	global_store_dwordx4 v[136:137], v[52:55], off offset:128
	global_store_dwordx4 v[136:137], v[48:51], off offset:192
	s_nop 1
	v_lshl_add_u64 v[136:137], v[136:137], 0, vcc
	global_load_dwordx4 v[172:175], v[134:135], off
	global_load_dwordx4 v[176:179], v[134:135], off offset:64
	global_load_dwordx4 v[220:223], v[134:135], off offset:128
	global_load_dwordx4 v[224:227], v[134:135], off offset:192
	s_waitcnt vmcnt(16)
	v_pk_fma_f32 v[44:45], v[44:45], v[140:141], v[228:229]
	v_pk_fma_f32 v[46:47], v[46:47], v[142:143], v[230:231]
	v_pk_fma_f32 v[40:41], v[40:41], v[144:145], v[232:233]
	v_pk_fma_f32 v[42:43], v[42:43], v[146:147], v[234:235]
	v_pk_fma_f32 v[36:37], v[36:37], v[148:149], v[236:237]
	v_pk_fma_f32 v[38:39], v[38:39], v[150:151], v[238:239]
	v_pk_fma_f32 v[32:33], v[32:33], v[152:153], v[240:241]
	v_pk_fma_f32 v[34:35], v[34:35], v[154:155], v[242:243]
	global_store_dwordx4 v[136:137], v[44:47], off
	global_store_dwordx4 v[136:137], v[40:43], off offset:64
	global_store_dwordx4 v[136:137], v[36:39], off offset:128
	global_store_dwordx4 v[136:137], v[32:35], off offset:192
	s_nop 1
	v_lshl_add_u64 v[136:137], v[136:137], 0, vcc
	s_waitcnt vmcnt(12)
	v_pk_fma_f32 v[28:29], v[28:29], v[140:141], v[156:157]
	v_pk_fma_f32 v[30:31], v[30:31], v[142:143], v[158:159]
	v_pk_fma_f32 v[24:25], v[24:25], v[144:145], v[160:161]
	v_pk_fma_f32 v[26:27], v[26:27], v[146:147], v[162:163]
	v_pk_fma_f32 v[20:21], v[20:21], v[148:149], v[164:165]
	v_pk_fma_f32 v[22:23], v[22:23], v[150:151], v[166:167]
	v_pk_fma_f32 v[16:17], v[16:17], v[152:153], v[168:169]
	v_pk_fma_f32 v[18:19], v[18:19], v[154:155], v[170:171]
	global_store_dwordx4 v[136:137], v[28:31], off
	global_store_dwordx4 v[136:137], v[24:27], off offset:64
	global_store_dwordx4 v[136:137], v[20:23], off offset:128
	global_store_dwordx4 v[136:137], v[16:19], off offset:192
	s_nop 1
	v_lshl_add_u64 v[136:137], v[136:137], 0, vcc
	s_waitcnt vmcnt(8)
	v_pk_fma_f32 v[12:13], v[12:13], v[140:141], v[172:173]
	v_pk_fma_f32 v[14:15], v[14:15], v[142:143], v[174:175]
	v_pk_fma_f32 v[8:9], v[8:9], v[144:145], v[176:177]
	v_pk_fma_f32 v[10:11], v[10:11], v[146:147], v[178:179]
	v_pk_fma_f32 v[4:5], v[4:5], v[148:149], v[220:221]
	v_pk_fma_f32 v[6:7], v[6:7], v[150:151], v[222:223]
	v_pk_fma_f32 v[0:1], v[0:1], v[152:153], v[224:225]
	v_pk_fma_f32 v[2:3], v[2:3], v[154:155], v[226:227]
	global_store_dwordx4 v[136:137], v[12:15], off
	global_store_dwordx4 v[136:137], v[8:11], off offset:64
	global_store_dwordx4 v[136:137], v[4:7], off offset:128
	global_store_dwordx4 v[136:137], v[0:3], off offset:192
	s_andn2_b64 vcc, exec, s[2:3]
	s_mov_b64 s[24:25], -1
	s_cbranch_vccz .LBB0_2324
	s_mov_b32 s72, s10
	s_mov_b32 s70, s18
	s_branch .LBB0_2279
